# post phase group-norm reductions: the xor-8/4/2/1 shuffle steps done with DPP row operations (row_mirror, row_half_mirror, quad_perm) instead of ds_bpermute round trips
# baseline (speedup 1.0000x reference)
.LBB0_503:
	v_mad_i64_i32 v[4:5], s[0:1], v82, s15, v[8:9]
	v_lshlrev_b64 v[4:5], 1, v[4:5]
	v_lshl_add_u64 v[14:15], s[10:11], 0, v[4:5]
	v_lshl_add_u64 v[4:5], s[12:13], 0, v[4:5]
	global_load_dwordx2 v[16:17], v[14:15], off nt
	global_load_dwordx2 v[22:23], v[4:5], off nt
	v_mov_b64_e32 v[6:7], s[76:77]
	v_mad_i64_i32 v[6:7], s[0:1], v82, s69, v[6:7]
	v_lshlrev_b32_e32 v144, 1, v8
	v_lshl_add_u64 v[6:7], v[6:7], 0, v[144:145]
	s_mov_b64 s[0:1], 0xb9a3000
	v_lshl_add_u64 v[12:13], v[6:7], 0, s[0:1]
	v_add_co_u32_e32 v6, vcc, 0xb9a3000, v6
	s_nop 1
	v_addc_co_u32_e32 v7, vcc, 0, v7, vcc
	global_load_dwordx2 v[34:35], v[6:7], off nt
	global_load_dwordx2 v[24:25], v[14:15], off offset:512 nt
	global_load_dwordx2 v[26:27], v[4:5], off offset:512 nt
	global_load_dwordx2 v[76:77], v[12:13], off offset:512 nt
	global_load_dwordx2 v[28:29], v[14:15], off offset:1024 nt
	global_load_dwordx2 v[30:31], v[4:5], off offset:1024 nt
	global_load_dwordx2 v[62:63], v[12:13], off offset:1024 nt
	global_load_dwordx2 v[32:33], v[14:15], off offset:1536 nt
	global_load_dwordx2 v[38:39], v[4:5], off offset:1536 nt
	global_load_dwordx2 v[56:57], v[12:13], off offset:1536 nt
	global_load_dwordx2 v[40:41], v[14:15], off offset:2048 nt
	global_load_dwordx2 v[46:47], v[4:5], off offset:2048 nt
	global_load_dwordx2 v[42:43], v[12:13], off offset:2048 nt
	global_load_dwordx2 v[48:49], v[14:15], off offset:2560 nt
	global_load_dwordx2 v[50:51], v[4:5], off offset:2560 nt
	global_load_dwordx2 v[36:37], v[12:13], off offset:2560 nt
	global_load_dwordx2 v[52:53], v[14:15], off offset:3072 nt
	global_load_dwordx2 v[54:55], v[4:5], off offset:3072 nt
	global_load_dwordx2 v[20:21], v[12:13], off offset:3072 nt
	s_nop 0
	global_load_dwordx2 v[14:15], v[14:15], off offset:3584 nt
	s_nop 0
	global_load_dwordx2 v[68:69], v[4:5], off offset:3584 nt
	global_load_dwordx2 v[18:19], v[12:13], off offset:3584 nt
	s_waitcnt vmcnt(21)
	v_lshlrev_b32_e32 v98, 16, v34
	v_mul_f32_e32 v100, 0xbfb8aa3b, v98
	v_exp_f32_e32 v100, v100
	v_and_b32_e32 v34, 0xffff0000, v34
	v_lshlrev_b32_e32 v99, 16, v35
	v_and_b32_e32 v35, 0xffff0000, v35
	v_add_f32_e32 v100, 1.0, v100
	v_lshlrev_b32_e32 v4, 16, v16
	v_and_b32_e32 v5, 0xffff0000, v16
	v_lshlrev_b32_e32 v6, 16, v22
	v_and_b32_e32 v7, 0xffff0000, v22
	v_pk_add_f32 v[4:5], v[4:5], v[6:7]
	v_lshlrev_b32_e32 v6, 16, v17
	v_and_b32_e32 v7, 0xffff0000, v17
	v_lshlrev_b32_e32 v12, 16, v23
	v_and_b32_e32 v13, 0xffff0000, v23
	v_pk_add_f32 v[6:7], v[6:7], v[12:13]
	v_add_f32_e32 v12, v4, v5
	v_add_f32_e32 v12, v6, v12
	v_add_f32_e32 v70, v7, v12
	s_waitcnt vmcnt(20)
	v_lshlrev_b32_e32 v12, 16, v24
	v_and_b32_e32 v13, 0xffff0000, v24
	s_waitcnt vmcnt(19)
	v_lshlrev_b32_e32 v16, 16, v26
	v_and_b32_e32 v17, 0xffff0000, v26
	v_pk_add_f32 v[80:81], v[12:13], v[16:17]
	v_lshlrev_b32_e32 v12, 16, v25
	v_and_b32_e32 v13, 0xffff0000, v25
	v_lshlrev_b32_e32 v16, 16, v27
	v_and_b32_e32 v17, 0xffff0000, v27
	v_pk_add_f32 v[78:79], v[12:13], v[16:17]
	v_add_f32_e32 v12, v80, v81
	v_add_f32_e32 v12, v78, v12
	v_add_f32_e32 v26, v79, v12
	s_waitcnt vmcnt(17)
	v_lshlrev_b32_e32 v12, 16, v28
	v_and_b32_e32 v13, 0xffff0000, v28
	s_waitcnt vmcnt(16)
	v_lshlrev_b32_e32 v16, 16, v30
	v_and_b32_e32 v17, 0xffff0000, v30
	v_pk_add_f32 v[64:65], v[12:13], v[16:17]
	v_lshlrev_b32_e32 v12, 16, v29
	v_and_b32_e32 v13, 0xffff0000, v29
	v_lshlrev_b32_e32 v16, 16, v31
	v_and_b32_e32 v17, 0xffff0000, v31
	v_pk_add_f32 v[66:67], v[12:13], v[16:17]
	v_add_f32_e32 v12, v64, v65
	v_add_f32_e32 v12, v66, v12
	v_add_f32_e32 v27, v67, v12
	s_waitcnt vmcnt(14)
	v_lshlrev_b32_e32 v12, 16, v32
	v_and_b32_e32 v13, 0xffff0000, v32
	ds_bpermute_b32 v32, v84, v26
	s_waitcnt vmcnt(13)
	v_lshlrev_b32_e32 v16, 16, v38
	v_and_b32_e32 v17, 0xffff0000, v38
	v_pk_add_f32 v[60:61], v[12:13], v[16:17]
	v_lshlrev_b32_e32 v12, 16, v33
	s_waitcnt lgkmcnt(0)
	v_add_f32_e32 v26, v26, v32
	ds_bpermute_b32 v32, v84, v27
	v_and_b32_e32 v13, 0xffff0000, v33
	v_lshlrev_b32_e32 v16, 16, v39
	v_and_b32_e32 v17, 0xffff0000, v39
	v_pk_add_f32 v[58:59], v[12:13], v[16:17]
	v_add_f32_e32 v12, v60, v61
	v_add_f32_e32 v12, v58, v12
	v_add_f32_e32 v28, v59, v12
	s_waitcnt vmcnt(11)
	v_lshlrev_b32_e32 v12, 16, v40
	v_and_b32_e32 v13, 0xffff0000, v40
	s_waitcnt vmcnt(10)
	v_lshlrev_b32_e32 v16, 16, v46
	v_and_b32_e32 v17, 0xffff0000, v46
	s_waitcnt lgkmcnt(0)
	v_add_f32_e32 v27, v27, v32
	ds_bpermute_b32 v32, v84, v28
	v_pk_add_f32 v[44:45], v[12:13], v[16:17]
	v_lshlrev_b32_e32 v12, 16, v41
	v_and_b32_e32 v13, 0xffff0000, v41
	v_lshlrev_b32_e32 v16, 16, v47
	v_and_b32_e32 v17, 0xffff0000, v47
	v_pk_add_f32 v[46:47], v[12:13], v[16:17]
	v_add_f32_e32 v12, v44, v45
	v_add_f32_e32 v12, v46, v12
	v_add_f32_e32 v29, v47, v12
	s_waitcnt vmcnt(8)
	v_lshlrev_b32_e32 v12, 16, v48
	v_and_b32_e32 v13, 0xffff0000, v48
	s_waitcnt vmcnt(7)
	v_lshlrev_b32_e32 v16, 16, v50
	v_and_b32_e32 v17, 0xffff0000, v50
	s_waitcnt lgkmcnt(0)
	v_add_f32_e32 v28, v28, v32
	ds_bpermute_b32 v32, v84, v29
	v_pk_add_f32 v[40:41], v[12:13], v[16:17]
	v_lshlrev_b32_e32 v12, 16, v49
	v_and_b32_e32 v13, 0xffff0000, v49
	v_lshlrev_b32_e32 v16, 16, v51
	v_and_b32_e32 v17, 0xffff0000, v51
	v_pk_add_f32 v[38:39], v[12:13], v[16:17]
	v_add_f32_e32 v12, v40, v41
	v_add_f32_e32 v12, v38, v12
	v_add_f32_e32 v30, v39, v12
	s_waitcnt vmcnt(5)
	v_lshlrev_b32_e32 v12, 16, v52
	v_and_b32_e32 v13, 0xffff0000, v52
	s_waitcnt vmcnt(4)
	v_lshlrev_b32_e32 v16, 16, v54
	v_and_b32_e32 v17, 0xffff0000, v54
	s_waitcnt lgkmcnt(0)
	v_add_f32_e32 v29, v29, v32
	ds_bpermute_b32 v32, v84, v30
	v_pk_add_f32 v[22:23], v[12:13], v[16:17]
	v_lshlrev_b32_e32 v12, 16, v53
	v_and_b32_e32 v13, 0xffff0000, v53
	v_lshlrev_b32_e32 v16, 16, v55
	v_and_b32_e32 v17, 0xffff0000, v55
	v_pk_add_f32 v[24:25], v[12:13], v[16:17]
	v_add_f32_e32 v12, v22, v23
	v_add_f32_e32 v12, v24, v12
	v_add_f32_e32 v31, v25, v12
	s_waitcnt vmcnt(2)
	v_lshlrev_b32_e32 v12, 16, v14
	v_and_b32_e32 v13, 0xffff0000, v14
	s_waitcnt vmcnt(1)
	v_lshlrev_b32_e32 v16, 16, v68
	v_and_b32_e32 v17, 0xffff0000, v68
	s_waitcnt lgkmcnt(0)
	v_add_f32_e32 v30, v30, v32
	ds_bpermute_b32 v32, v84, v31
	v_pk_add_f32 v[16:17], v[12:13], v[16:17]
	v_lshlrev_b32_e32 v12, 16, v15
	v_and_b32_e32 v13, 0xffff0000, v15
	v_lshlrev_b32_e32 v14, 16, v69
	v_and_b32_e32 v15, 0xffff0000, v69
	v_pk_add_f32 v[14:15], v[12:13], v[14:15]
	v_add_f32_e32 v12, v16, v17
	v_add_f32_e32 v12, v14, v12
	v_add_f32_e32 v12, v15, v12
	ds_bpermute_b32 v13, v84, v70
	s_waitcnt lgkmcnt(0)
	v_add_f32_e32 v31, v31, v32
	ds_bpermute_b32 v32, v84, v12
	v_div_scale_f32 v101, s[0:1], v100, v100, v98
	s_waitcnt lgkmcnt(0)
	v_add_f32_e32 v13, v70, v13
	v_rcp_f32_e32 v102, v101
	s_waitcnt lgkmcnt(0)
	v_add_f32_e32 v12, v12, v32
	ds_bpermute_b32 v32, v85, v13
	v_fma_f32 v103, -v101, v102, 1.0
	v_fmac_f32_e32 v102, v103, v102
	v_div_scale_f32 v103, vcc, v98, v100, v98
	s_waitcnt lgkmcnt(0)
	v_add_f32_e32 v13, v13, v32
	ds_bpermute_b32 v32, v85, v26
	v_mul_f32_e32 v104, v103, v102
	v_fma_f32 v105, -v101, v104, v103
	v_fmac_f32_e32 v104, v105, v102
	v_fma_f32 v101, -v101, v104, v103
	s_waitcnt lgkmcnt(0)
	v_add_f32_e32 v26, v26, v32
	ds_bpermute_b32 v32, v85, v27
	v_div_fmas_f32 v101, v101, v102, v104
	v_div_fixup_f32 v98, v101, v100, v98
	v_mul_f32_e32 v100, 0xbfb8aa3b, v34
	v_exp_f32_e32 v100, v100
	s_waitcnt lgkmcnt(0)
	v_add_f32_e32 v27, v27, v32
	ds_bpermute_b32 v32, v85, v28
	v_add_f32_e32 v100, 1.0, v100
	v_div_scale_f32 v101, s[0:1], v100, v100, v34
	s_waitcnt lgkmcnt(0)
	v_add_f32_e32 v28, v28, v32
	ds_bpermute_b32 v32, v85, v29
	v_rcp_f32_e32 v102, v101
	s_waitcnt lgkmcnt(0)
	v_add_f32_e32 v29, v29, v32
	ds_bpermute_b32 v32, v85, v30
	v_fma_f32 v103, -v101, v102, 1.0
	v_fmac_f32_e32 v102, v103, v102
	v_div_scale_f32 v103, vcc, v34, v100, v34
	s_waitcnt lgkmcnt(0)
	v_add_f32_e32 v30, v30, v32
	ds_bpermute_b32 v32, v85, v31
	v_mul_f32_e32 v104, v103, v102
	v_fma_f32 v105, -v101, v104, v103
	v_fmac_f32_e32 v104, v105, v102
	v_fma_f32 v101, -v101, v104, v103
	s_waitcnt lgkmcnt(0)
	v_add_f32_e32 v31, v31, v32
	ds_bpermute_b32 v32, v85, v12
	v_div_fmas_f32 v101, v101, v102, v104
	v_div_fixup_f32 v100, v101, v100, v34
	v_mul_f32_e32 v34, 0xbfb8aa3b, v99
	v_exp_f32_e32 v34, v34
	s_waitcnt lgkmcnt(0)
	v_add_f32_e32 v12, v12, v32
	v_add_f32_e32 v34, 1.0, v34
	v_div_scale_f32 v101, s[0:1], v34, v34, v99
	s_waitcnt lgkmcnt(0)
	s_nop 1
	v_add_f32_dpp v13, v13, v13 row_mirror row_mask:0xf bank_mask:0xf
	v_rcp_f32_e32 v102, v101
	s_waitcnt lgkmcnt(0)
	s_nop 1
	v_add_f32_dpp v26, v26, v26 row_mirror row_mask:0xf bank_mask:0xf
	v_fma_f32 v103, -v101, v102, 1.0
	v_fmac_f32_e32 v102, v103, v102
	v_div_scale_f32 v103, vcc, v99, v34, v99
	s_waitcnt lgkmcnt(0)
	s_nop 1
	v_add_f32_dpp v27, v27, v27 row_mirror row_mask:0xf bank_mask:0xf
	v_mul_f32_e32 v104, v103, v102
	v_fma_f32 v105, -v101, v104, v103
	v_fmac_f32_e32 v104, v105, v102
	v_fma_f32 v101, -v101, v104, v103
	s_waitcnt lgkmcnt(0)
	s_nop 1
	v_add_f32_dpp v28, v28, v28 row_mirror row_mask:0xf bank_mask:0xf
	v_div_fmas_f32 v101, v101, v102, v104
	v_div_fixup_f32 v99, v101, v34, v99
	v_mul_f32_e32 v34, 0xbfb8aa3b, v35
	v_exp_f32_e32 v34, v34
	s_waitcnt lgkmcnt(0)
	s_nop 1
	v_add_f32_dpp v29, v29, v29 row_mirror row_mask:0xf bank_mask:0xf
	v_add_f32_e32 v34, 1.0, v34
	v_div_scale_f32 v101, s[0:1], v34, v34, v35
	s_waitcnt lgkmcnt(0)
	s_nop 1
	v_add_f32_dpp v30, v30, v30 row_mirror row_mask:0xf bank_mask:0xf
	v_rcp_f32_e32 v102, v101
	s_waitcnt lgkmcnt(0)
	s_nop 1
	v_add_f32_dpp v31, v31, v31 row_mirror row_mask:0xf bank_mask:0xf
	v_fma_f32 v103, -v101, v102, 1.0
	v_fmac_f32_e32 v102, v103, v102
	v_div_scale_f32 v103, vcc, v35, v34, v35
	s_waitcnt lgkmcnt(0)
	s_nop 1
	v_add_f32_dpp v12, v12, v12 row_mirror row_mask:0xf bank_mask:0xf
	v_mul_f32_e32 v104, v103, v102
	v_fma_f32 v105, -v101, v104, v103
	v_fmac_f32_e32 v104, v105, v102
	v_fma_f32 v101, -v101, v104, v103
	s_waitcnt lgkmcnt(0)
	s_nop 1
	v_add_f32_dpp v13, v13, v13 row_half_mirror row_mask:0xf bank_mask:0xf
	v_div_fmas_f32 v101, v101, v102, v104
	v_div_fixup_f32 v101, v101, v34, v35
	s_waitcnt lgkmcnt(0)
	s_nop 1
	v_add_f32_dpp v26, v26, v26 row_half_mirror row_mask:0xf bank_mask:0xf
	s_waitcnt lgkmcnt(0)
	s_nop 1
	v_add_f32_dpp v27, v27, v27 row_half_mirror row_mask:0xf bank_mask:0xf
	s_waitcnt lgkmcnt(0)
	s_nop 1
	v_add_f32_dpp v28, v28, v28 row_half_mirror row_mask:0xf bank_mask:0xf
	s_waitcnt lgkmcnt(0)
	s_nop 1
	v_add_f32_dpp v29, v29, v29 row_half_mirror row_mask:0xf bank_mask:0xf
	s_waitcnt lgkmcnt(0)
	s_nop 1
	v_add_f32_dpp v30, v30, v30 row_half_mirror row_mask:0xf bank_mask:0xf
	s_waitcnt lgkmcnt(0)
	s_nop 1
	v_add_f32_dpp v31, v31, v31 row_half_mirror row_mask:0xf bank_mask:0xf
	s_waitcnt lgkmcnt(0)
	s_nop 1
	v_add_f32_dpp v12, v12, v12 row_half_mirror row_mask:0xf bank_mask:0xf
	s_waitcnt lgkmcnt(0)
	s_nop 1
	v_add_f32_dpp v13, v13, v13 quad_perm:[2,3,0,1] row_mask:0xf bank_mask:0xf
	s_waitcnt lgkmcnt(0)
	s_nop 1
	v_add_f32_dpp v26, v26, v26 quad_perm:[2,3,0,1] row_mask:0xf bank_mask:0xf
	s_waitcnt lgkmcnt(0)
	s_nop 1
	v_add_f32_dpp v27, v27, v27 quad_perm:[2,3,0,1] row_mask:0xf bank_mask:0xf
	s_waitcnt lgkmcnt(0)
	s_nop 1
	v_add_f32_dpp v28, v28, v28 quad_perm:[2,3,0,1] row_mask:0xf bank_mask:0xf
	s_waitcnt lgkmcnt(0)
	s_nop 1
	v_add_f32_dpp v29, v29, v29 quad_perm:[2,3,0,1] row_mask:0xf bank_mask:0xf
	s_waitcnt lgkmcnt(0)
	s_nop 1
	v_add_f32_dpp v30, v30, v30 quad_perm:[2,3,0,1] row_mask:0xf bank_mask:0xf
	s_waitcnt lgkmcnt(0)
	s_nop 1
	v_add_f32_dpp v31, v31, v31 quad_perm:[2,3,0,1] row_mask:0xf bank_mask:0xf
	s_waitcnt lgkmcnt(0)
	s_nop 1
	v_add_f32_dpp v12, v12, v12 quad_perm:[2,3,0,1] row_mask:0xf bank_mask:0xf
	s_waitcnt lgkmcnt(0)
	s_nop 1
	v_add_f32_dpp v13, v13, v13 quad_perm:[1,0,3,2] row_mask:0xf bank_mask:0xf
	v_fmamk_f32 v5, v13, 0xbb800000, v5
	v_fmac_f32_e32 v4, 0xbb800000, v13
	v_fmamk_f32 v7, v13, 0xbb800000, v7
	v_fmac_f32_e32 v6, 0xbb800000, v13
	s_waitcnt lgkmcnt(0)
	s_nop 1
	v_add_f32_dpp v26, v26, v26 quad_perm:[1,0,3,2] row_mask:0xf bank_mask:0xf
	v_fmamk_f32 v81, v26, 0xbb800000, v81
	v_fmac_f32_e32 v80, 0xbb800000, v26
	v_pk_mul_f32 v[92:93], v[4:5], v[4:5]
	v_fmamk_f32 v79, v26, 0xbb800000, v79
	v_fmac_f32_e32 v78, 0xbb800000, v26
	v_pk_mul_f32 v[96:97], v[80:81], v[80:81]
	v_pk_mul_f32 v[90:91], v[6:7], v[6:7]
	v_pk_mul_f32 v[94:95], v[78:79], v[78:79]
	v_mov_b32_e32 v34, v96
	v_mov_b32_e32 v35, v92
	v_mov_b32_e32 v92, v97
	v_pk_add_f32 v[34:35], v[34:35], v[92:93]
	v_mov_b32_e32 v92, v94
	v_mov_b32_e32 v93, v90
	v_pk_add_f32 v[34:35], v[92:93], v[34:35]
	v_mov_b32_e32 v90, v95
	v_pk_add_f32 v[34:35], v[90:91], v[34:35]
	ds_bpermute_b32 v91, v84, v35
	ds_bpermute_b32 v90, v84, v34
	s_waitcnt lgkmcnt(0)
	v_pk_add_f32 v[34:35], v[34:35], v[90:91]
	ds_bpermute_b32 v91, v85, v35
	ds_bpermute_b32 v90, v85, v34
	s_waitcnt lgkmcnt(0)
	s_nop 1
	v_add_f32_dpp v27, v27, v27 quad_perm:[1,0,3,2] row_mask:0xf bank_mask:0xf
	v_fmamk_f32 v65, v27, 0xbb800000, v65
	v_fmac_f32_e32 v64, 0xbb800000, v27
	s_waitcnt lgkmcnt(0)
	v_pk_add_f32 v[34:35], v[34:35], v[90:91]
	s_waitcnt lgkmcnt(0)
	s_nop 1
	v_add_f32_dpp v28, v28, v28 quad_perm:[1,0,3,2] row_mask:0xf bank_mask:0xf
	v_fmamk_f32 v61, v28, 0xbb800000, v61
	v_fmac_f32_e32 v60, 0xbb800000, v28
	v_fmamk_f32 v67, v27, 0xbb800000, v67
	s_waitcnt lgkmcnt(0)
	s_nop 1
	v_add_f32_dpp v29, v29, v29 quad_perm:[1,0,3,2] row_mask:0xf bank_mask:0xf
	s_waitcnt lgkmcnt(0)
	s_nop 1
	v_add_f32_dpp v35, v35, v35 row_mirror row_mask:0xf bank_mask:0xf
	v_add_f32_dpp v34, v34, v34 row_mirror row_mask:0xf bank_mask:0xf
	v_fmac_f32_e32 v66, 0xbb800000, v27
	s_waitcnt lgkmcnt(0)
	s_nop 1
	v_add_f32_dpp v30, v30, v30 quad_perm:[1,0,3,2] row_mask:0xf bank_mask:0xf
	v_pk_mul_f32 v[70:71], v[64:65], v[64:65]
	s_waitcnt lgkmcnt(0)
	s_nop 1
	v_add_f32_dpp v35, v35, v35 row_half_mirror row_mask:0xf bank_mask:0xf
	v_add_f32_dpp v34, v34, v34 row_half_mirror row_mask:0xf bank_mask:0xf
	s_waitcnt lgkmcnt(0)
	s_nop 1
	v_add_f32_dpp v31, v31, v31 quad_perm:[1,0,3,2] row_mask:0xf bank_mask:0xf
	v_fmamk_f32 v59, v28, 0xbb800000, v59
	v_fmac_f32_e32 v58, 0xbb800000, v28
	s_waitcnt lgkmcnt(0)
	s_nop 1
	v_add_f32_dpp v35, v35, v35 quad_perm:[2,3,0,1] row_mask:0xf bank_mask:0xf
	v_add_f32_dpp v34, v34, v34 quad_perm:[2,3,0,1] row_mask:0xf bank_mask:0xf
	s_waitcnt lgkmcnt(0)
	s_nop 1
	v_add_f32_dpp v12, v12, v12 quad_perm:[1,0,3,2] row_mask:0xf bank_mask:0xf
	v_fmamk_f32 v17, v12, 0xbb800000, v17
	v_fmac_f32_e32 v16, 0xbb800000, v12
	v_fmamk_f32 v15, v12, 0xbb800000, v15
	v_fmac_f32_e32 v14, 0xbb800000, v12
	v_mad_i64_i32 v[12:13], s[0:1], v82, s70, v[10:11]
	s_mov_b32 s0, 0x358637bd
	s_waitcnt lgkmcnt(0)
	s_nop 1
	v_add_f32_dpp v91, v35, v35 quad_perm:[1,0,3,2] row_mask:0xf bank_mask:0xf
	v_add_f32_dpp v90, v34, v34 quad_perm:[1,0,3,2] row_mask:0xf bank_mask:0xf
	v_mov_b64_e32 v[34:35], s[0:1]
	v_pk_fma_f32 v[90:91], v[90:91], s[34:35], v[34:35] op_sel_hi:[1,0,0]
	v_pk_mul_f32 v[74:75], v[60:61], v[60:61]
	v_mul_f32_e32 v92, 0x4b800000, v91
	v_cmp_gt_f32_e64 s[0:1], s72, v91
	v_cmp_gt_f32_e32 vcc, s72, v90
	v_pk_mul_f32 v[68:69], v[66:67], v[66:67]
	v_cndmask_b32_e64 v91, v91, v92, s[0:1]
	v_rsq_f32_e32 v91, v91
	v_pk_mul_f32 v[72:73], v[58:59], v[58:59]
	v_fmamk_f32 v45, v29, 0xbb800000, v45
	v_fmac_f32_e32 v44, 0xbb800000, v29
	v_mul_f32_e32 v92, 0x45800000, v91
	v_cndmask_b32_e64 v91, v91, v92, s[0:1]
	v_mul_f32_e32 v4, v4, v91
	v_mul_f32_e32 v5, v5, v91
	v_mul_f32_e32 v4, v0, v4
	v_mul_f32_e32 v5, v1, v5
	v_mul_f32_e32 v4, v98, v4
	v_mul_f32_e32 v5, v100, v5
	v_cvt_pk_bf16_f32 v4, v4, v5
	v_mul_f32_e32 v5, v6, v91
	v_mul_f32_e32 v5, v2, v5
	v_mul_f32_e32 v6, v7, v91
	v_mul_f32_e32 v5, v99, v5
	v_mul_f32_e32 v6, v3, v6
	v_mul_f32_e32 v6, v101, v6
	v_cvt_pk_bf16_f32 v5, v5, v6
	global_store_dwordx2 v[12:13], v[4:5], off
	v_mul_f32_e32 v4, 0x4b800000, v90
	v_cndmask_b32_e32 v4, v90, v4, vcc
	v_rsq_f32_e32 v4, v4
	v_lshlrev_b32_e32 v91, 16, v76
	v_and_b32_e32 v76, 0xffff0000, v76
	v_lshlrev_b32_e32 v92, 16, v77
	v_mul_f32_e32 v5, 0x45800000, v4
	v_cndmask_b32_e32 v90, v4, v5, vcc
	ds_read_b128 v[4:7], v83 offset:1024
	v_mul_f32_e32 v80, v80, v90
	v_and_b32_e32 v77, 0xffff0000, v77
	v_fmamk_f32 v41, v30, 0xbb800000, v41
	v_fmac_f32_e32 v40, 0xbb800000, v30
	s_waitcnt lgkmcnt(0)
	v_mul_f32_e32 v4, v80, v4
	v_mul_f32_e32 v80, 0xbfb8aa3b, v91
	v_exp_f32_e32 v80, v80
	v_fmamk_f32 v47, v29, 0xbb800000, v47
	v_fmac_f32_e32 v46, 0xbb800000, v29
	v_pk_mul_f32 v[50:51], v[44:45], v[44:45]
	v_add_f32_e32 v80, 1.0, v80
	v_div_scale_f32 v93, s[0:1], v80, v80, v91
	v_rcp_f32_e32 v94, v93
	v_fmamk_f32 v39, v30, 0xbb800000, v39
	v_fmac_f32_e32 v38, 0xbb800000, v30
	v_pk_mul_f32 v[54:55], v[40:41], v[40:41]
	v_fma_f32 v95, -v93, v94, 1.0
	v_fmac_f32_e32 v94, v95, v94
	v_div_scale_f32 v95, vcc, v91, v80, v91
	v_mul_f32_e32 v96, v95, v94
	v_fma_f32 v97, -v93, v96, v95
	v_fmac_f32_e32 v96, v97, v94
	v_fma_f32 v93, -v93, v96, v95
	v_div_fmas_f32 v93, v93, v94, v96
	v_div_fixup_f32 v80, v93, v80, v91
	v_mul_f32_e32 v4, v80, v4
	v_mul_f32_e32 v80, v81, v90
	v_mul_f32_e32 v5, v80, v5
	v_mul_f32_e32 v80, 0xbfb8aa3b, v76
	v_exp_f32_e32 v80, v80
	v_pk_mul_f32 v[48:49], v[46:47], v[46:47]
	v_pk_mul_f32 v[52:53], v[38:39], v[38:39]
	v_fmamk_f32 v23, v31, 0xbb800000, v23
	v_add_f32_e32 v80, 1.0, v80
	v_div_scale_f32 v81, s[0:1], v80, v80, v76
	v_rcp_f32_e32 v91, v81
	v_fmac_f32_e32 v22, 0xbb800000, v31
	v_fmamk_f32 v25, v31, 0xbb800000, v25
	v_fmac_f32_e32 v24, 0xbb800000, v31
	v_fma_f32 v93, -v81, v91, 1.0
	v_fmac_f32_e32 v91, v93, v91
	v_div_scale_f32 v93, vcc, v76, v80, v76
	v_mul_f32_e32 v94, v93, v91
	v_fma_f32 v95, -v81, v94, v93
	v_fmac_f32_e32 v94, v95, v91
	v_fma_f32 v81, -v81, v94, v93
	v_div_fmas_f32 v81, v81, v91, v94
	v_div_fixup_f32 v76, v81, v80, v76
	v_mul_f32_e32 v5, v76, v5
	v_cvt_pk_bf16_f32 v4, v4, v5
	v_mul_f32_e32 v5, v78, v90
	v_mul_f32_e32 v5, v5, v6
	v_mul_f32_e32 v6, 0xbfb8aa3b, v92
	v_exp_f32_e32 v6, v6
	v_pk_mul_f32 v[28:29], v[22:23], v[22:23]
	v_pk_mul_f32 v[32:33], v[16:17], v[16:17]
	v_pk_mul_f32 v[26:27], v[24:25], v[24:25]
	v_add_f32_e32 v6, 1.0, v6
	v_div_scale_f32 v76, s[0:1], v6, v6, v92
	v_rcp_f32_e32 v78, v76
	v_pk_mul_f32 v[30:31], v[14:15], v[14:15]
	v_add_u32_e32 v82, s14, v82
	v_fma_f32 v80, -v76, v78, 1.0
	v_fmac_f32_e32 v78, v80, v78
	v_div_scale_f32 v80, vcc, v92, v6, v92
	v_mul_f32_e32 v81, v80, v78
	v_fma_f32 v91, -v76, v81, v80
	v_fmac_f32_e32 v81, v91, v78
	v_fma_f32 v76, -v76, v81, v80
	v_div_fmas_f32 v76, v76, v78, v81
	v_div_fixup_f32 v6, v76, v6, v92
	v_mul_f32_e32 v5, v6, v5
	v_mul_f32_e32 v6, v79, v90
	v_mul_f32_e32 v6, v6, v7
	v_mul_f32_e32 v7, 0xbfb8aa3b, v77
	v_exp_f32_e32 v7, v7
	s_nop 0
	v_add_f32_e32 v7, 1.0, v7
	v_div_scale_f32 v76, s[0:1], v7, v7, v77
	v_rcp_f32_e32 v78, v76
	s_nop 0
	v_fma_f32 v79, -v76, v78, 1.0
	v_fmac_f32_e32 v78, v79, v78
	v_div_scale_f32 v79, vcc, v77, v7, v77
	v_mul_f32_e32 v80, v79, v78
	v_fma_f32 v81, -v76, v80, v79
	v_fmac_f32_e32 v80, v81, v78
	v_fma_f32 v76, -v76, v80, v79
	v_div_fmas_f32 v76, v76, v78, v80
	v_div_fixup_f32 v7, v76, v7, v77
	v_lshlrev_b32_e32 v76, 16, v62
	v_mul_f32_e32 v78, 0xbfb8aa3b, v76
	v_exp_f32_e32 v78, v78
	v_and_b32_e32 v62, 0xffff0000, v62
	v_lshlrev_b32_e32 v77, 16, v63
	v_and_b32_e32 v63, 0xffff0000, v63
	v_add_f32_e32 v78, 1.0, v78
	v_div_scale_f32 v79, s[0:1], v78, v78, v76
	v_rcp_f32_e32 v80, v79
	v_mul_f32_e32 v6, v7, v6
	v_cvt_pk_bf16_f32 v5, v5, v6
	global_store_dwordx2 v[12:13], v[4:5], off offset:512
	v_fma_f32 v81, -v79, v80, 1.0
	v_fmac_f32_e32 v80, v81, v80
	v_div_scale_f32 v81, vcc, v76, v78, v76
	v_mul_f32_e32 v90, v81, v80
	v_fma_f32 v91, -v79, v90, v81
	v_fmac_f32_e32 v90, v91, v80
	v_fma_f32 v79, -v79, v90, v81
	v_div_fmas_f32 v79, v79, v80, v90
	v_div_fixup_f32 v76, v79, v78, v76
	v_mul_f32_e32 v78, 0xbfb8aa3b, v62
	v_exp_f32_e32 v78, v78
	ds_read_b128 v[4:7], v83 offset:2048
	v_add_f32_e32 v78, 1.0, v78
	v_div_scale_f32 v79, s[0:1], v78, v78, v62
	v_rcp_f32_e32 v80, v79
	s_nop 0
	v_fma_f32 v81, -v79, v80, 1.0
	v_fmac_f32_e32 v80, v81, v80
	v_div_scale_f32 v81, vcc, v62, v78, v62
	v_mul_f32_e32 v90, v81, v80
	v_fma_f32 v91, -v79, v90, v81
	v_fmac_f32_e32 v90, v91, v80
	v_fma_f32 v79, -v79, v90, v81
	v_div_fmas_f32 v79, v79, v80, v90
	v_div_fixup_f32 v78, v79, v78, v62
	v_mul_f32_e32 v62, 0xbfb8aa3b, v77
	v_exp_f32_e32 v62, v62
	s_nop 0
	v_add_f32_e32 v62, 1.0, v62
	v_div_scale_f32 v79, s[0:1], v62, v62, v77
	v_rcp_f32_e32 v80, v79
	s_nop 0
	v_fma_f32 v81, -v79, v80, 1.0
	v_fmac_f32_e32 v80, v81, v80
	v_div_scale_f32 v81, vcc, v77, v62, v77
	v_mul_f32_e32 v90, v81, v80
	v_fma_f32 v91, -v79, v90, v81
	v_fmac_f32_e32 v90, v91, v80
	v_fma_f32 v79, -v79, v90, v81
	v_div_fmas_f32 v79, v79, v80, v90
	v_div_fixup_f32 v77, v79, v62, v77
	v_mul_f32_e32 v62, 0xbfb8aa3b, v63
	v_exp_f32_e32 v62, v62
	s_nop 0
	v_add_f32_e32 v62, 1.0, v62
	v_div_scale_f32 v79, s[0:1], v62, v62, v63
	v_rcp_f32_e32 v80, v79
	s_nop 0
	v_fma_f32 v81, -v79, v80, 1.0
	v_fmac_f32_e32 v80, v81, v80
	v_div_scale_f32 v81, vcc, v63, v62, v63
	v_mul_f32_e32 v90, v81, v80
	v_fma_f32 v91, -v79, v90, v81
	v_fmac_f32_e32 v90, v91, v80
	v_fma_f32 v79, -v79, v90, v81
	v_div_fmas_f32 v79, v79, v80, v90
	v_div_fixup_f32 v79, v79, v62, v63
	v_mov_b32_e32 v62, v74
	v_mov_b32_e32 v63, v70
	v_mov_b32_e32 v70, v75
	v_pk_add_f32 v[62:63], v[62:63], v[70:71]
	v_mov_b32_e32 v70, v72
	v_mov_b32_e32 v71, v68
	v_pk_add_f32 v[62:63], v[70:71], v[62:63]
	v_mov_b32_e32 v68, v73
	v_pk_add_f32 v[62:63], v[68:69], v[62:63]
	ds_bpermute_b32 v69, v84, v63
	ds_bpermute_b32 v68, v84, v62
	s_waitcnt lgkmcnt(0)
	v_pk_add_f32 v[62:63], v[62:63], v[68:69]
	ds_bpermute_b32 v69, v85, v63
	ds_bpermute_b32 v68, v85, v62
	s_waitcnt lgkmcnt(0)
	v_pk_add_f32 v[62:63], v[62:63], v[68:69]
	s_waitcnt lgkmcnt(0)
	s_nop 1
	v_add_f32_dpp v63, v63, v63 row_mirror row_mask:0xf bank_mask:0xf
	v_add_f32_dpp v62, v62, v62 row_mirror row_mask:0xf bank_mask:0xf
	s_waitcnt lgkmcnt(0)
	s_nop 1
	v_add_f32_dpp v63, v63, v63 row_half_mirror row_mask:0xf bank_mask:0xf
	v_add_f32_dpp v62, v62, v62 row_half_mirror row_mask:0xf bank_mask:0xf
	s_waitcnt lgkmcnt(0)
	s_nop 1
	v_add_f32_dpp v63, v63, v63 quad_perm:[2,3,0,1] row_mask:0xf bank_mask:0xf
	v_add_f32_dpp v62, v62, v62 quad_perm:[2,3,0,1] row_mask:0xf bank_mask:0xf
	s_waitcnt lgkmcnt(0)
	s_nop 1
	v_add_f32_dpp v63, v63, v63 quad_perm:[1,0,3,2] row_mask:0xf bank_mask:0xf
	v_add_f32_dpp v62, v62, v62 quad_perm:[1,0,3,2] row_mask:0xf bank_mask:0xf
	s_nop 0
	v_pk_fma_f32 v[62:63], v[62:63], s[34:35], v[34:35] op_sel_hi:[1,0,0]
	s_nop 0
	v_mul_f32_e32 v68, 0x4b800000, v63
	v_cmp_gt_f32_e64 s[0:1], s72, v63
	v_cmp_gt_f32_e32 vcc, s72, v62
	s_nop 0
	v_cndmask_b32_e64 v63, v63, v68, s[0:1]
	v_rsq_f32_e32 v63, v63
	s_nop 0
	v_mul_f32_e32 v68, 0x45800000, v63
	v_cndmask_b32_e64 v63, v63, v68, s[0:1]
	v_mul_f32_e32 v64, v64, v63
	v_mul_f32_e32 v4, v64, v4
	v_mul_f32_e32 v64, v65, v63
	v_mul_f32_e32 v5, v64, v5
	v_mul_f32_e32 v4, v76, v4
	v_mul_f32_e32 v5, v78, v5
	v_cvt_pk_bf16_f32 v4, v4, v5
	v_mul_f32_e32 v5, v66, v63
	v_mul_f32_e32 v5, v5, v6
	v_mul_f32_e32 v6, v67, v63
	v_mul_f32_e32 v5, v77, v5
	v_mul_f32_e32 v6, v6, v7
	v_mul_f32_e32 v6, v79, v6
	v_cvt_pk_bf16_f32 v5, v5, v6
	global_store_dwordx2 v[12:13], v[4:5], off offset:1024
	v_mul_f32_e32 v4, 0x4b800000, v62
	v_cndmask_b32_e32 v4, v62, v4, vcc
	v_rsq_f32_e32 v4, v4
	v_lshlrev_b32_e32 v63, 16, v56
	v_and_b32_e32 v56, 0xffff0000, v56
	v_lshlrev_b32_e32 v64, 16, v57
	v_mul_f32_e32 v5, 0x45800000, v4
	v_cndmask_b32_e32 v62, v4, v5, vcc
	ds_read_b128 v[4:7], v83 offset:3072
	v_mul_f32_e32 v60, v60, v62
	v_and_b32_e32 v57, 0xffff0000, v57
	s_waitcnt lgkmcnt(0)
	v_mul_f32_e32 v4, v60, v4
	v_mul_f32_e32 v60, 0xbfb8aa3b, v63
	v_exp_f32_e32 v60, v60
	s_nop 0
	v_add_f32_e32 v60, 1.0, v60
	v_div_scale_f32 v65, s[0:1], v60, v60, v63
	v_rcp_f32_e32 v66, v65
	s_nop 0
	v_fma_f32 v67, -v65, v66, 1.0
	v_fmac_f32_e32 v66, v67, v66
	v_div_scale_f32 v67, vcc, v63, v60, v63
	v_mul_f32_e32 v68, v67, v66
	v_fma_f32 v69, -v65, v68, v67
	v_fmac_f32_e32 v68, v69, v66
	v_fma_f32 v65, -v65, v68, v67
	v_div_fmas_f32 v65, v65, v66, v68
	v_div_fixup_f32 v60, v65, v60, v63
	v_mul_f32_e32 v4, v60, v4
	v_mul_f32_e32 v60, v61, v62
	v_mul_f32_e32 v5, v60, v5
	v_mul_f32_e32 v60, 0xbfb8aa3b, v56
	v_exp_f32_e32 v60, v60
	s_nop 0
	v_add_f32_e32 v60, 1.0, v60
	v_div_scale_f32 v61, s[0:1], v60, v60, v56
	v_rcp_f32_e32 v63, v61
	s_nop 0
	v_fma_f32 v65, -v61, v63, 1.0
	v_fmac_f32_e32 v63, v65, v63
	v_div_scale_f32 v65, vcc, v56, v60, v56
	v_mul_f32_e32 v66, v65, v63
	v_fma_f32 v67, -v61, v66, v65
	v_fmac_f32_e32 v66, v67, v63
	v_fma_f32 v61, -v61, v66, v65
	v_div_fmas_f32 v61, v61, v63, v66
	v_div_fixup_f32 v56, v61, v60, v56
	v_mul_f32_e32 v5, v56, v5
	v_cvt_pk_bf16_f32 v4, v4, v5
	v_mul_f32_e32 v5, v58, v62
	v_mul_f32_e32 v5, v5, v6
	v_mul_f32_e32 v6, 0xbfb8aa3b, v64
	v_exp_f32_e32 v6, v6
	s_nop 0
	v_add_f32_e32 v6, 1.0, v6
	v_div_scale_f32 v56, s[0:1], v6, v6, v64
	v_rcp_f32_e32 v58, v56
	s_nop 0
	v_fma_f32 v60, -v56, v58, 1.0
	v_fmac_f32_e32 v58, v60, v58
	v_div_scale_f32 v60, vcc, v64, v6, v64
	v_mul_f32_e32 v61, v60, v58
	v_fma_f32 v63, -v56, v61, v60
	v_fmac_f32_e32 v61, v63, v58
	v_fma_f32 v56, -v56, v61, v60
	v_div_fmas_f32 v56, v56, v58, v61
	v_div_fixup_f32 v6, v56, v6, v64
	v_mul_f32_e32 v5, v6, v5
	v_mul_f32_e32 v6, v59, v62
	v_mul_f32_e32 v6, v6, v7
	v_mul_f32_e32 v7, 0xbfb8aa3b, v57
	v_exp_f32_e32 v7, v7
	s_nop 0
	v_add_f32_e32 v7, 1.0, v7
	v_div_scale_f32 v56, s[0:1], v7, v7, v57
	v_rcp_f32_e32 v58, v56
	s_nop 0
	v_fma_f32 v59, -v56, v58, 1.0
	v_fmac_f32_e32 v58, v59, v58
	v_div_scale_f32 v59, vcc, v57, v7, v57
	v_mul_f32_e32 v60, v59, v58
	v_fma_f32 v61, -v56, v60, v59
	v_fmac_f32_e32 v60, v61, v58
	v_fma_f32 v56, -v56, v60, v59
	v_div_fmas_f32 v56, v56, v58, v60
	v_div_fixup_f32 v7, v56, v7, v57
	v_lshlrev_b32_e32 v56, 16, v42
	v_mul_f32_e32 v58, 0xbfb8aa3b, v56
	v_exp_f32_e32 v58, v58
	v_and_b32_e32 v42, 0xffff0000, v42
	v_lshlrev_b32_e32 v57, 16, v43
	v_and_b32_e32 v43, 0xffff0000, v43
	v_add_f32_e32 v58, 1.0, v58
	v_div_scale_f32 v59, s[0:1], v58, v58, v56
	v_rcp_f32_e32 v60, v59
	v_mul_f32_e32 v6, v7, v6
	v_cvt_pk_bf16_f32 v5, v5, v6
	global_store_dwordx2 v[12:13], v[4:5], off offset:1536
	v_fma_f32 v61, -v59, v60, 1.0
	v_fmac_f32_e32 v60, v61, v60
	v_div_scale_f32 v61, vcc, v56, v58, v56
	v_mul_f32_e32 v62, v61, v60
	v_fma_f32 v63, -v59, v62, v61
	v_fmac_f32_e32 v62, v63, v60
	v_fma_f32 v59, -v59, v62, v61
	v_div_fmas_f32 v59, v59, v60, v62
	v_div_fixup_f32 v56, v59, v58, v56
	v_mul_f32_e32 v58, 0xbfb8aa3b, v42
	v_exp_f32_e32 v58, v58
	ds_read_b128 v[4:7], v83 offset:4096
	v_add_f32_e32 v58, 1.0, v58
	v_div_scale_f32 v59, s[0:1], v58, v58, v42
	v_rcp_f32_e32 v60, v59
	s_nop 0
	v_fma_f32 v61, -v59, v60, 1.0
	v_fmac_f32_e32 v60, v61, v60
	v_div_scale_f32 v61, vcc, v42, v58, v42
	v_mul_f32_e32 v62, v61, v60
	v_fma_f32 v63, -v59, v62, v61
	v_fmac_f32_e32 v62, v63, v60
	v_fma_f32 v59, -v59, v62, v61
	v_div_fmas_f32 v59, v59, v60, v62
	v_div_fixup_f32 v58, v59, v58, v42
	v_mul_f32_e32 v42, 0xbfb8aa3b, v57
	v_exp_f32_e32 v42, v42
	s_nop 0
	v_add_f32_e32 v42, 1.0, v42
	v_div_scale_f32 v59, s[0:1], v42, v42, v57
	v_rcp_f32_e32 v60, v59
	s_nop 0
	v_fma_f32 v61, -v59, v60, 1.0
	v_fmac_f32_e32 v60, v61, v60
	v_div_scale_f32 v61, vcc, v57, v42, v57
	v_mul_f32_e32 v62, v61, v60
	v_fma_f32 v63, -v59, v62, v61
	v_fmac_f32_e32 v62, v63, v60
	v_fma_f32 v59, -v59, v62, v61
	v_div_fmas_f32 v59, v59, v60, v62
	v_div_fixup_f32 v57, v59, v42, v57
	v_mul_f32_e32 v42, 0xbfb8aa3b, v43
	v_exp_f32_e32 v42, v42
	s_nop 0
	v_add_f32_e32 v42, 1.0, v42
	v_div_scale_f32 v59, s[0:1], v42, v42, v43
	v_rcp_f32_e32 v60, v59
	s_nop 0
	v_fma_f32 v61, -v59, v60, 1.0
	v_fmac_f32_e32 v60, v61, v60
	v_div_scale_f32 v61, vcc, v43, v42, v43
	v_mul_f32_e32 v62, v61, v60
	v_fma_f32 v63, -v59, v62, v61
	v_fmac_f32_e32 v62, v63, v60
	v_fma_f32 v59, -v59, v62, v61
	v_div_fmas_f32 v59, v59, v60, v62
	v_div_fixup_f32 v59, v59, v42, v43
	v_mov_b32_e32 v42, v54
	v_mov_b32_e32 v43, v50
	v_mov_b32_e32 v50, v55
	v_pk_add_f32 v[42:43], v[42:43], v[50:51]
	v_mov_b32_e32 v50, v52
	v_mov_b32_e32 v51, v48
	v_pk_add_f32 v[42:43], v[50:51], v[42:43]
	v_mov_b32_e32 v48, v53
	v_pk_add_f32 v[42:43], v[48:49], v[42:43]
	ds_bpermute_b32 v49, v84, v43
	ds_bpermute_b32 v48, v84, v42
	s_waitcnt lgkmcnt(0)
	v_pk_add_f32 v[42:43], v[42:43], v[48:49]
	ds_bpermute_b32 v49, v85, v43
	ds_bpermute_b32 v48, v85, v42
	s_waitcnt lgkmcnt(0)
	v_pk_add_f32 v[42:43], v[42:43], v[48:49]
	s_waitcnt lgkmcnt(0)
	s_nop 1
	v_add_f32_dpp v43, v43, v43 row_mirror row_mask:0xf bank_mask:0xf
	v_add_f32_dpp v42, v42, v42 row_mirror row_mask:0xf bank_mask:0xf
	s_waitcnt lgkmcnt(0)
	s_nop 1
	v_add_f32_dpp v43, v43, v43 row_half_mirror row_mask:0xf bank_mask:0xf
	v_add_f32_dpp v42, v42, v42 row_half_mirror row_mask:0xf bank_mask:0xf
	s_waitcnt lgkmcnt(0)
	s_nop 1
	v_add_f32_dpp v43, v43, v43 quad_perm:[2,3,0,1] row_mask:0xf bank_mask:0xf
	v_add_f32_dpp v42, v42, v42 quad_perm:[2,3,0,1] row_mask:0xf bank_mask:0xf
	s_waitcnt lgkmcnt(0)
	s_nop 1
	v_add_f32_dpp v43, v43, v43 quad_perm:[1,0,3,2] row_mask:0xf bank_mask:0xf
	v_add_f32_dpp v42, v42, v42 quad_perm:[1,0,3,2] row_mask:0xf bank_mask:0xf
	s_nop 0
	v_pk_fma_f32 v[42:43], v[42:43], s[34:35], v[34:35] op_sel_hi:[1,0,0]
	s_nop 0
	v_mul_f32_e32 v48, 0x4b800000, v43
	v_cmp_gt_f32_e64 s[0:1], s72, v43
	v_cmp_gt_f32_e32 vcc, s72, v42
	s_nop 0
	v_cndmask_b32_e64 v43, v43, v48, s[0:1]
	v_rsq_f32_e32 v43, v43
	s_nop 0
	v_mul_f32_e32 v48, 0x45800000, v43
	v_cndmask_b32_e64 v43, v43, v48, s[0:1]
	v_mul_f32_e32 v44, v44, v43
	v_mul_f32_e32 v4, v44, v4
	v_mul_f32_e32 v44, v45, v43
	v_mul_f32_e32 v5, v44, v5
	v_mul_f32_e32 v4, v56, v4
	v_mul_f32_e32 v5, v58, v5
	v_cvt_pk_bf16_f32 v4, v4, v5
	v_mul_f32_e32 v5, v46, v43
	v_mul_f32_e32 v5, v5, v6
	v_mul_f32_e32 v6, v47, v43
	v_mul_f32_e32 v5, v57, v5
	v_mul_f32_e32 v6, v6, v7
	v_mul_f32_e32 v6, v59, v6
	v_cvt_pk_bf16_f32 v5, v5, v6
	global_store_dwordx2 v[12:13], v[4:5], off offset:2048
	v_mul_f32_e32 v4, 0x4b800000, v42
	v_cndmask_b32_e32 v4, v42, v4, vcc
	v_rsq_f32_e32 v4, v4
	v_lshlrev_b32_e32 v43, 16, v36
	v_and_b32_e32 v36, 0xffff0000, v36
	v_lshlrev_b32_e32 v44, 16, v37
	v_mul_f32_e32 v5, 0x45800000, v4
	v_cndmask_b32_e32 v42, v4, v5, vcc
	ds_read_b128 v[4:7], v83 offset:5120
	v_mul_f32_e32 v40, v40, v42
	v_and_b32_e32 v37, 0xffff0000, v37
	s_waitcnt lgkmcnt(0)
	v_mul_f32_e32 v4, v40, v4
	v_mul_f32_e32 v40, 0xbfb8aa3b, v43
	v_exp_f32_e32 v40, v40
	s_nop 0
	v_add_f32_e32 v40, 1.0, v40
	v_div_scale_f32 v45, s[0:1], v40, v40, v43
	v_rcp_f32_e32 v46, v45
	s_nop 0
	v_fma_f32 v47, -v45, v46, 1.0
	v_fmac_f32_e32 v46, v47, v46
	v_div_scale_f32 v47, vcc, v43, v40, v43
	v_mul_f32_e32 v48, v47, v46
	v_fma_f32 v49, -v45, v48, v47
	v_fmac_f32_e32 v48, v49, v46
	v_fma_f32 v45, -v45, v48, v47
	v_div_fmas_f32 v45, v45, v46, v48
	v_div_fixup_f32 v40, v45, v40, v43
	v_mul_f32_e32 v4, v40, v4
	v_mul_f32_e32 v40, v41, v42
	v_mul_f32_e32 v5, v40, v5
	v_mul_f32_e32 v40, 0xbfb8aa3b, v36
	v_exp_f32_e32 v40, v40
	s_nop 0
	v_add_f32_e32 v40, 1.0, v40
	v_div_scale_f32 v41, s[0:1], v40, v40, v36
	v_rcp_f32_e32 v43, v41
	s_nop 0
	v_fma_f32 v45, -v41, v43, 1.0
	v_fmac_f32_e32 v43, v45, v43
	v_div_scale_f32 v45, vcc, v36, v40, v36
	v_mul_f32_e32 v46, v45, v43
	v_fma_f32 v47, -v41, v46, v45
	v_fmac_f32_e32 v46, v47, v43
	v_fma_f32 v41, -v41, v46, v45
	v_div_fmas_f32 v41, v41, v43, v46
	v_div_fixup_f32 v36, v41, v40, v36
	v_mul_f32_e32 v5, v36, v5
	v_cvt_pk_bf16_f32 v4, v4, v5
	v_mul_f32_e32 v5, v38, v42
	v_mul_f32_e32 v5, v5, v6
	v_mul_f32_e32 v6, 0xbfb8aa3b, v44
	v_exp_f32_e32 v6, v6
	s_nop 0
	v_add_f32_e32 v6, 1.0, v6
	v_div_scale_f32 v36, s[0:1], v6, v6, v44
	v_rcp_f32_e32 v38, v36
	s_nop 0
	v_fma_f32 v40, -v36, v38, 1.0
	v_fmac_f32_e32 v38, v40, v38
	v_div_scale_f32 v40, vcc, v44, v6, v44
	v_mul_f32_e32 v41, v40, v38
	v_fma_f32 v43, -v36, v41, v40
	v_fmac_f32_e32 v41, v43, v38
	v_fma_f32 v36, -v36, v41, v40
	v_div_fmas_f32 v36, v36, v38, v41
	v_div_fixup_f32 v6, v36, v6, v44
	v_mul_f32_e32 v5, v6, v5
	v_mul_f32_e32 v6, v39, v42
	v_mul_f32_e32 v6, v6, v7
	v_mul_f32_e32 v7, 0xbfb8aa3b, v37
	v_exp_f32_e32 v7, v7
	s_nop 0
	v_add_f32_e32 v7, 1.0, v7
	v_div_scale_f32 v36, s[0:1], v7, v7, v37
	v_rcp_f32_e32 v38, v36
	s_nop 0
	v_fma_f32 v39, -v36, v38, 1.0
	v_fmac_f32_e32 v38, v39, v38
	v_div_scale_f32 v39, vcc, v37, v7, v37
	v_mul_f32_e32 v40, v39, v38
	v_fma_f32 v41, -v36, v40, v39
	v_fmac_f32_e32 v40, v41, v38
	v_fma_f32 v36, -v36, v40, v39
	v_div_fmas_f32 v36, v36, v38, v40
	v_div_fixup_f32 v7, v36, v7, v37
	v_lshlrev_b32_e32 v36, 16, v20
	v_mul_f32_e32 v38, 0xbfb8aa3b, v36
	v_exp_f32_e32 v38, v38
	v_and_b32_e32 v20, 0xffff0000, v20
	v_lshlrev_b32_e32 v37, 16, v21
	v_and_b32_e32 v21, 0xffff0000, v21
	v_add_f32_e32 v38, 1.0, v38
	v_div_scale_f32 v39, s[0:1], v38, v38, v36
	v_rcp_f32_e32 v40, v39
	v_mul_f32_e32 v6, v7, v6
	v_cvt_pk_bf16_f32 v5, v5, v6
	global_store_dwordx2 v[12:13], v[4:5], off offset:2560
	v_fma_f32 v41, -v39, v40, 1.0
	v_fmac_f32_e32 v40, v41, v40
	v_div_scale_f32 v41, vcc, v36, v38, v36
	v_mul_f32_e32 v42, v41, v40
	v_fma_f32 v43, -v39, v42, v41
	v_fmac_f32_e32 v42, v43, v40
	v_fma_f32 v39, -v39, v42, v41
	v_div_fmas_f32 v39, v39, v40, v42
	v_div_fixup_f32 v36, v39, v38, v36
	v_mul_f32_e32 v38, 0xbfb8aa3b, v20
	v_exp_f32_e32 v38, v38
	ds_read_b128 v[4:7], v83 offset:6144
	v_add_f32_e32 v38, 1.0, v38
	v_div_scale_f32 v39, s[0:1], v38, v38, v20
	v_rcp_f32_e32 v40, v39
	s_nop 0
	v_fma_f32 v41, -v39, v40, 1.0
	v_fmac_f32_e32 v40, v41, v40
	v_div_scale_f32 v41, vcc, v20, v38, v20
	v_mul_f32_e32 v42, v41, v40
	v_fma_f32 v43, -v39, v42, v41
	v_fmac_f32_e32 v42, v43, v40
	v_fma_f32 v39, -v39, v42, v41
	v_div_fmas_f32 v39, v39, v40, v42
	v_div_fixup_f32 v38, v39, v38, v20
	v_mul_f32_e32 v20, 0xbfb8aa3b, v37
	v_exp_f32_e32 v20, v20
	s_nop 0
	v_add_f32_e32 v20, 1.0, v20
	v_div_scale_f32 v39, s[0:1], v20, v20, v37
	v_rcp_f32_e32 v40, v39
	s_nop 0
	v_fma_f32 v41, -v39, v40, 1.0
	v_fmac_f32_e32 v40, v41, v40
	v_div_scale_f32 v41, vcc, v37, v20, v37
	v_mul_f32_e32 v42, v41, v40
	v_fma_f32 v43, -v39, v42, v41
	v_fmac_f32_e32 v42, v43, v40
	v_fma_f32 v39, -v39, v42, v41
	v_div_fmas_f32 v39, v39, v40, v42
	v_div_fixup_f32 v37, v39, v20, v37
	v_mul_f32_e32 v20, 0xbfb8aa3b, v21
	v_exp_f32_e32 v20, v20
	s_nop 0
	v_add_f32_e32 v20, 1.0, v20
	v_div_scale_f32 v39, s[0:1], v20, v20, v21
	v_rcp_f32_e32 v40, v39
	s_nop 0
	v_fma_f32 v41, -v39, v40, 1.0
	v_fmac_f32_e32 v40, v41, v40
	v_div_scale_f32 v41, vcc, v21, v20, v21
	v_mul_f32_e32 v42, v41, v40
	v_fma_f32 v43, -v39, v42, v41
	v_fmac_f32_e32 v42, v43, v40
	v_fma_f32 v39, -v39, v42, v41
	v_div_fmas_f32 v39, v39, v40, v42
	v_div_fixup_f32 v39, v39, v20, v21
	v_mov_b32_e32 v20, v32
	v_mov_b32_e32 v21, v28
	v_mov_b32_e32 v28, v33
	v_pk_add_f32 v[20:21], v[20:21], v[28:29]
	v_mov_b32_e32 v28, v30
	v_mov_b32_e32 v29, v26
	v_pk_add_f32 v[20:21], v[28:29], v[20:21]
	v_mov_b32_e32 v26, v31
	v_pk_add_f32 v[20:21], v[26:27], v[20:21]
	ds_bpermute_b32 v27, v84, v21
	ds_bpermute_b32 v26, v84, v20
	s_waitcnt lgkmcnt(0)
	v_pk_add_f32 v[20:21], v[20:21], v[26:27]
	ds_bpermute_b32 v27, v85, v21
	ds_bpermute_b32 v26, v85, v20
	s_waitcnt lgkmcnt(0)
	v_pk_add_f32 v[20:21], v[20:21], v[26:27]
	s_waitcnt lgkmcnt(0)
	s_nop 1
	v_add_f32_dpp v21, v21, v21 row_mirror row_mask:0xf bank_mask:0xf
	v_add_f32_dpp v20, v20, v20 row_mirror row_mask:0xf bank_mask:0xf
	s_waitcnt lgkmcnt(0)
	s_nop 1
	v_add_f32_dpp v21, v21, v21 row_half_mirror row_mask:0xf bank_mask:0xf
	v_add_f32_dpp v20, v20, v20 row_half_mirror row_mask:0xf bank_mask:0xf
	s_waitcnt lgkmcnt(0)
	s_nop 1
	v_add_f32_dpp v21, v21, v21 quad_perm:[2,3,0,1] row_mask:0xf bank_mask:0xf
	v_add_f32_dpp v20, v20, v20 quad_perm:[2,3,0,1] row_mask:0xf bank_mask:0xf
	s_waitcnt lgkmcnt(0)
	s_nop 1
	v_add_f32_dpp v21, v21, v21 quad_perm:[1,0,3,2] row_mask:0xf bank_mask:0xf
	v_add_f32_dpp v20, v20, v20 quad_perm:[1,0,3,2] row_mask:0xf bank_mask:0xf
	s_nop 0
	v_pk_fma_f32 v[20:21], v[20:21], s[34:35], v[34:35] op_sel_hi:[1,0,0]
	s_nop 0
	v_mul_f32_e32 v26, 0x4b800000, v21
	v_cmp_gt_f32_e64 s[0:1], s72, v21
	v_cmp_gt_f32_e32 vcc, s72, v20
	s_nop 0
	v_cndmask_b32_e64 v21, v21, v26, s[0:1]
	v_rsq_f32_e32 v21, v21
	s_nop 0
	v_mul_f32_e32 v26, 0x45800000, v21
	v_cndmask_b32_e64 v21, v21, v26, s[0:1]
	v_mul_f32_e32 v22, v22, v21
	v_mul_f32_e32 v4, v22, v4
	v_mul_f32_e32 v22, v23, v21
	v_mul_f32_e32 v5, v22, v5
	v_mul_f32_e32 v4, v36, v4
	v_mul_f32_e32 v5, v38, v5
	v_cvt_pk_bf16_f32 v4, v4, v5
	v_mul_f32_e32 v5, v24, v21
	v_mul_f32_e32 v5, v5, v6
	v_mul_f32_e32 v6, v25, v21
	v_mul_f32_e32 v5, v37, v5
	v_mul_f32_e32 v6, v6, v7
	v_mul_f32_e32 v6, v39, v6
	v_cvt_pk_bf16_f32 v5, v5, v6
	global_store_dwordx2 v[12:13], v[4:5], off offset:3072
	v_mul_f32_e32 v4, 0x4b800000, v20
	v_cndmask_b32_e32 v4, v20, v4, vcc
	v_rsq_f32_e32 v4, v4
	s_waitcnt vmcnt(7)
	v_lshlrev_b32_e32 v21, 16, v18
	v_and_b32_e32 v22, 0xffff0000, v18
	v_lshlrev_b32_e32 v23, 16, v19
	v_mul_f32_e32 v5, 0x45800000, v4
	v_cndmask_b32_e32 v20, v4, v5, vcc
	ds_read_b128 v[4:7], v83 offset:7168
	v_mul_f32_e32 v16, v16, v20
	v_and_b32_e32 v18, 0xffff0000, v19
	s_waitcnt lgkmcnt(0)
	v_mul_f32_e32 v4, v16, v4
	v_mul_f32_e32 v16, 0xbfb8aa3b, v21
	v_exp_f32_e32 v16, v16
	s_nop 0
	v_add_f32_e32 v16, 1.0, v16
	v_div_scale_f32 v19, s[0:1], v16, v16, v21
	v_rcp_f32_e32 v24, v19
	s_nop 0
	v_fma_f32 v25, -v19, v24, 1.0
	v_fmac_f32_e32 v24, v25, v24
	v_div_scale_f32 v25, vcc, v21, v16, v21
	v_mul_f32_e32 v26, v25, v24
	v_fma_f32 v27, -v19, v26, v25
	v_fmac_f32_e32 v26, v27, v24
	v_fma_f32 v19, -v19, v26, v25
	v_div_fmas_f32 v19, v19, v24, v26
	v_div_fixup_f32 v16, v19, v16, v21
	v_mul_f32_e32 v4, v16, v4
	v_mul_f32_e32 v16, v17, v20
	v_mul_f32_e32 v5, v16, v5
	v_mul_f32_e32 v16, 0xbfb8aa3b, v22
	v_exp_f32_e32 v16, v16
	s_nop 0
	v_add_f32_e32 v16, 1.0, v16
	v_div_scale_f32 v17, s[0:1], v16, v16, v22
	v_rcp_f32_e32 v19, v17
	s_nop 0
	v_fma_f32 v21, -v17, v19, 1.0
	v_fmac_f32_e32 v19, v21, v19
	v_div_scale_f32 v21, vcc, v22, v16, v22
	v_mul_f32_e32 v24, v21, v19
	v_fma_f32 v25, -v17, v24, v21
	v_fmac_f32_e32 v24, v25, v19
	v_fma_f32 v17, -v17, v24, v21
	v_div_fmas_f32 v17, v17, v19, v24
	v_div_fixup_f32 v16, v17, v16, v22
	v_mul_f32_e32 v5, v16, v5
	v_cvt_pk_bf16_f32 v4, v4, v5
	v_mul_f32_e32 v5, v14, v20
	v_mul_f32_e32 v5, v5, v6
	v_mul_f32_e32 v6, 0xbfb8aa3b, v23
	v_exp_f32_e32 v6, v6
	s_nop 0
	v_add_f32_e32 v6, 1.0, v6
	v_div_scale_f32 v14, s[0:1], v6, v6, v23
	v_rcp_f32_e32 v16, v14
	s_nop 0
	v_fma_f32 v17, -v14, v16, 1.0
	v_fmac_f32_e32 v16, v17, v16
	v_div_scale_f32 v17, vcc, v23, v6, v23
	v_mul_f32_e32 v19, v17, v16
	v_fma_f32 v21, -v14, v19, v17
	v_fmac_f32_e32 v19, v21, v16
	v_fma_f32 v14, -v14, v19, v17
	v_div_fmas_f32 v14, v14, v16, v19
	v_div_fixup_f32 v6, v14, v6, v23
	v_mul_f32_e32 v5, v6, v5
	v_mul_f32_e32 v6, v15, v20
	v_mul_f32_e32 v6, v6, v7
	v_mul_f32_e32 v7, 0xbfb8aa3b, v18
	v_exp_f32_e32 v7, v7
	s_nop 0
	v_add_f32_e32 v7, 1.0, v7
	v_div_scale_f32 v15, s[0:1], v7, v7, v18
	v_rcp_f32_e32 v14, v15
	s_movk_i32 s0, 0x1fff
	v_fma_f32 v16, -v15, v14, 1.0
	v_fmac_f32_e32 v14, v16, v14
	v_div_scale_f32 v16, vcc, v18, v7, v18
	v_mul_f32_e32 v17, v16, v14
	v_fma_f32 v19, -v15, v17, v16
	v_fmac_f32_e32 v17, v19, v14
	v_fma_f32 v15, -v15, v17, v16
	v_div_fmas_f32 v14, v15, v14, v17
	v_cmp_lt_i32_e32 vcc, s0, v82
	v_div_fixup_f32 v7, v14, v7, v18
	s_or_b64 s[6:7], vcc, s[6:7]
	v_mul_f32_e32 v6, v7, v6
	v_cvt_pk_bf16_f32 v5, v5, v6
	global_store_dwordx2 v[12:13], v[4:5], off offset:3584
	s_andn2_b64 exec, exec, s[6:7]
	s_cbranch_execnz .LBB0_503
